# P1 K-loop: last 3 LDS-DMA pieces of the super-phase-2 load segment issued between the MFMAs of the following block (vmcnt(8)->vmcnt(5) in that segment)
# speedup vs baseline: 1.0080x; 1.0031x over previous
; #define PG8_STAGE(bufoff, gbase, voff) do { _Pragma("unroll") for (int _i = 0; _i < 2; ++_i) \
;         __builtin_amdgcn_global_load_lds((const unsigned*)((const char*)(gbase) + (voff)[_i]), (PG8_LAS unsigned*)(lds + (bufoff) + ldsw + _i * 8192), 16, 0, 0); } while (0)
; #define PG8_LDA(dst, b, h) do { _Pragma("unroll") for (int m = 0; m < 4; ++m) _Pragma("unroll") for (int k = 0; k < 2; ++k) dst[m][k] = *(const PG8_LAS bf16x8*)(lds + PG8_SA(b, h) + aoff + m * 2048 + k * 1024); } while (0)
; #define PG8_LDB(dst, b, h) do { _Pragma("unroll") for (int n = 0; n < 2; ++n) _Pragma("unroll") for (int k = 0; k < 2; ++k) dst[n][k] = *(const PG8_LAS bf16x8*)(lds + PG8_SB(b, h) + boff + n * 2048 + k * 1024); } while (0)
; #define PG8_MMA(ai, bj, At, Bt) do { __builtin_amdgcn_s_setprio(1); _Pragma("unroll") for (int m = 0; m < 4; ++m) _Pragma("unroll") for (int n = 0; n < 2; ++n) _Pragma("unroll") for (int k = 0; k < 2; ++k) \
;         acc[ai][bj][m][n] = __builtin_amdgcn_mfma_f32_16x16x32_bf16(Bt[n][k], At[m][k], acc[ai][bj][m][n], 0, 0, 0); __builtin_amdgcn_s_setprio(0); } while (0)
; #define PG8_WAIT_V(n) asm volatile("s_waitcnt vmcnt(" #n ")" ::: "memory")
; #define PG8_WAIT_L(n) asm volatile("s_waitcnt lgkmcnt(" #n ")" ::: "memory")
; #define PG8_BAR __builtin_amdgcn_s_barrier()
; #define PG8_SCHED __builtin_amdgcn_sched_barrier(0)
; template <class Epi, class Sched, bool ALIGN_EPI = false, bool SP2 = false>
; __device__ __forceinline__ void gemm_phase(PG8_LAS unsigned char* lds, const Gemm g, const Sched& S, const Epi& E) {
;     ...
;             PG8_LDB(B0, 0, 0); PG8_LDB(B1, 0, 1); PG8_SCHED; PG8_LDA(At, 0, 0); PG8_STAGE(PG8_SA(1, 1), a1 + hstep, voffA);
;             PG8_WAIT_V(8); PG8_WAIT_L(0); PG8_BAR; PG8_MMA(0, 0, At, B0); PG8_MMA(0, 1, At, B1); PG8_BAR; PG8_SCHED;
;             PG8_LDA(At, 0, 1); PG8_STAGE(PG8_SB(0, 0), b2, voffB); PG8_STAGE(PG8_SB(0, 1), b2 + hstep, voffB); PG8_STAGE(PG8_SA(0, 0), a2, voffA);
;             PG8_WAIT_V(8); PG8_WAIT_L(0); PG8_BAR; PG8_MMA(1, 0, At, B0); PG8_MMA(1, 1, At, B1); PG8_BAR; PG8_SCHED;
.LBB0_126:
	ds_read_b128 v[128:131], v177
	ds_read_b128 v[132:135], v177 offset:1024
	ds_read_b128 v[136:139], v177 offset:2048
	ds_read_b128 v[140:143], v177 offset:3072
	ds_read_b128 v[168:171], v178
	ds_read_b128 v[182:185], v178 offset:1024
	ds_read_b128 v[190:193], v178 offset:2048
	ds_read_b128 v[194:197], v178 offset:3072
	s_add_u32 s42, s40, 0xfffc0080
	s_addc_u32 s43, s41, -1
	s_cmp_eq_u32 vcc_hi, 12
	s_cselect_b32 s45, s35, s43
	s_cselect_b32 s44, s95, s42
	s_cselect_b32 s43, s31, vcc_lo
	s_cselect_b32 s42, s96, s97
	v_lshl_add_u64 v[172:173], s[40:41], 0, v[160:161]
	s_add_i32 m0, s53, 0xc000
	ds_read_b128 v[198:201], v179
	ds_read_b128 v[202:205], v179 offset:1024
	ds_read_b128 v[206:209], v179 offset:2048
	ds_read_b128 v[210:213], v179 offset:3072
	ds_read_b128 v[214:217], v179 offset:4096
	ds_read_b128 v[218:221], v179 offset:5120
	ds_read_b128 v[222:225], v179 offset:6144
	ds_read_b128 v[226:229], v179 offset:7168
	global_load_lds_dwordx4 v[172:173], off
	v_lshl_add_u64 v[172:173], s[40:41], 0, v[162:163]
	s_add_i32 m0, s53, 0xe000
	s_nop 0
	global_load_lds_dwordx4 v[172:173], off
	s_waitcnt vmcnt(8)
	s_waitcnt lgkmcnt(0)
	s_barrier
	s_setprio 1
	s_waitcnt lgkmcnt(0)
	v_mfma_f32_16x16x32_bf16 v[124:127], v[128:131], v[198:201], v[124:127]
	v_mfma_f32_16x16x32_bf16 v[120:123], v[136:139], v[198:201], v[120:123]
	v_mfma_f32_16x16x32_bf16 v[108:111], v[128:131], v[206:209], v[108:111]
	v_mfma_f32_16x16x32_bf16 v[104:107], v[136:139], v[206:209], v[104:107]
	v_mfma_f32_16x16x32_bf16 v[96:99], v[128:131], v[214:217], v[96:99]
	v_mfma_f32_16x16x32_bf16 v[88:91], v[136:139], v[214:217], v[88:91]
	v_mfma_f32_16x16x32_bf16 v[80:83], v[128:131], v[222:225], v[80:83]
	v_mfma_f32_16x16x32_bf16 v[72:75], v[136:139], v[222:225], v[72:75]
	v_mfma_f32_16x16x32_bf16 v[124:127], v[132:135], v[202:205], v[124:127]
	v_mfma_f32_16x16x32_bf16 v[120:123], v[140:143], v[202:205], v[120:123]
	v_mfma_f32_16x16x32_bf16 v[108:111], v[132:135], v[210:213], v[108:111]
	v_mfma_f32_16x16x32_bf16 v[104:107], v[140:143], v[210:213], v[104:107]
	v_mfma_f32_16x16x32_bf16 v[96:99], v[132:135], v[218:221], v[96:99]
	v_mfma_f32_16x16x32_bf16 v[88:91], v[140:143], v[218:221], v[88:91]
	v_mfma_f32_16x16x32_bf16 v[80:83], v[132:135], v[226:229], v[80:83]
	v_mfma_f32_16x16x32_bf16 v[72:75], v[140:143], v[226:229], v[72:75]
	s_setprio 0
	s_setprio 1
	v_mfma_f32_16x16x32_bf16 v[116:119], v[168:171], v[198:201], v[116:119]
	v_mfma_f32_16x16x32_bf16 v[112:115], v[190:193], v[198:201], v[112:115]
	v_mfma_f32_16x16x32_bf16 v[100:103], v[168:171], v[206:209], v[100:103]
	v_mfma_f32_16x16x32_bf16 v[92:95], v[190:193], v[206:209], v[92:95]
	v_mfma_f32_16x16x32_bf16 v[84:87], v[168:171], v[214:217], v[84:87]
	v_mfma_f32_16x16x32_bf16 v[76:79], v[190:193], v[214:217], v[76:79]
	v_mfma_f32_16x16x32_bf16 v[68:71], v[168:171], v[222:225], v[68:71]
	v_mfma_f32_16x16x32_bf16 v[64:67], v[190:193], v[222:225], v[64:67]
	v_mfma_f32_16x16x32_bf16 v[116:119], v[182:185], v[202:205], v[116:119]
	v_mfma_f32_16x16x32_bf16 v[112:115], v[194:197], v[202:205], v[112:115]
	v_mfma_f32_16x16x32_bf16 v[100:103], v[182:185], v[210:213], v[100:103]
	v_mfma_f32_16x16x32_bf16 v[92:95], v[194:197], v[210:213], v[92:95]
	v_mfma_f32_16x16x32_bf16 v[84:87], v[182:185], v[218:221], v[84:87]
	v_mfma_f32_16x16x32_bf16 v[76:79], v[194:197], v[218:221], v[76:79]
	v_mfma_f32_16x16x32_bf16 v[68:71], v[182:185], v[226:229], v[68:71]
	v_mfma_f32_16x16x32_bf16 v[64:67], v[194:197], v[226:229], v[64:67]
	s_setprio 0
	s_barrier
	s_add_i32 s54, s71, s50
	v_lshl_add_u64 v[172:173], s[42:43], 0, v[146:147]
	s_mov_b32 m0, s54
	ds_read_b128 v[198:201], v179 offset:16384
	ds_read_b128 v[202:205], v179 offset:17408
	ds_read_b128 v[206:209], v179 offset:18432
	ds_read_b128 v[210:213], v179 offset:19456
	ds_read_b128 v[214:217], v179 offset:20480
	ds_read_b128 v[218:221], v179 offset:21504
	ds_read_b128 v[222:225], v179 offset:22528
	ds_read_b128 v[226:229], v179 offset:23552
	global_load_lds_dwordx4 v[172:173], off
	s_add_i32 m0, s54, 0x2000
	s_add_u32 s84, s42, 0x40000
	v_lshl_add_u64 v[186:187], s[42:43], 0, v[150:151]
	s_addc_u32 s85, s43, 0
	s_add_i32 s54, s72, s50
	global_load_lds_dwordx4 v[186:187], off
	v_lshl_add_u64 v[230:231], s[84:85], 0, v[146:147]
	s_mov_b32 m0, s54
	v_lshl_add_u64 v[232:233], s[44:45], 0, v[148:149]
	global_load_lds_dwordx4 v[230:231], off
	s_waitcnt vmcnt(5)
	s_waitcnt lgkmcnt(0)
	s_barrier
; #define PG8_STAGE(bufoff, gbase, voff) do { _Pragma("unroll") for (int _i = 0; _i < 2; ++_i) \
;         __builtin_amdgcn_global_load_lds((const unsigned*)((const char*)(gbase) + (voff)[_i]), (PG8_LAS unsigned*)(lds + (bufoff) + ldsw + _i * 8192), 16, 0, 0); } while (0)
; #define PG8_LDA(dst, b, h) do { _Pragma("unroll") for (int m = 0; m < 4; ++m) _Pragma("unroll") for (int k = 0; k < 2; ++k) dst[m][k] = *(const PG8_LAS bf16x8*)(lds + PG8_SA(b, h) + aoff + m * 2048 + k * 1024); } while (0)
; #define PG8_LDB(dst, b, h) do { _Pragma("unroll") for (int n = 0; n < 2; ++n) _Pragma("unroll") for (int k = 0; k < 2; ++k) dst[n][k] = *(const PG8_LAS bf16x8*)(lds + PG8_SB(b, h) + boff + n * 2048 + k * 1024); } while (0)
; #define PG8_MMA(ai, bj, At, Bt) do { __builtin_amdgcn_s_setprio(1); _Pragma("unroll") for (int m = 0; m < 4; ++m) _Pragma("unroll") for (int n = 0; n < 2; ++n) _Pragma("unroll") for (int k = 0; k < 2; ++k) \
;         acc[ai][bj][m][n] = __builtin_amdgcn_mfma_f32_16x16x32_bf16(Bt[n][k], At[m][k], acc[ai][bj][m][n], 0, 0, 0); __builtin_amdgcn_s_setprio(0); } while (0)
; #define PG8_WAIT_V(n) asm volatile("s_waitcnt vmcnt(" #n ")" ::: "memory")
; #define PG8_WAIT_L(n) asm volatile("s_waitcnt lgkmcnt(" #n ")" ::: "memory")
; #define PG8_BAR __builtin_amdgcn_s_barrier()
; #define PG8_SCHED __builtin_amdgcn_sched_barrier(0)
; template <class Epi, class Sched, bool ALIGN_EPI = false, bool SP2 = false>
; __device__ __forceinline__ void gemm_phase(PG8_LAS unsigned char* lds, const Gemm g, const Sched& S, const Epi& E) {
;     ...
;             PG8_WAIT_V(8); PG8_WAIT_L(0); PG8_BAR; PG8_MMA(0, 0, At, B0); PG8_MMA(0, 1, At, B1); PG8_BAR; PG8_SCHED;
;             PG8_LDA(At, 0, 1); PG8_STAGE(PG8_SB(0, 0), b2, voffB); PG8_STAGE(PG8_SB(0, 1), b2 + hstep, voffB); PG8_STAGE(PG8_SA(0, 0), a2, voffA);
;             PG8_WAIT_V(8); PG8_WAIT_L(0); PG8_BAR; PG8_MMA(1, 0, At, B0); PG8_MMA(1, 1, At, B1); PG8_BAR; PG8_SCHED;
;             PG8_LDB(B0, 1, 0); PG8_LDB(B1, 1, 1); PG8_SCHED; PG8_LDA(At, 1, 0); PG8_STAGE(PG8_SA(0, 1), a2 + hstep, voffA);
;             PG8_WAIT_V(8); PG8_WAIT_L(0); PG8_BAR; PG8_MMA(0, 0, At, B0); PG8_MMA(0, 1, At, B1); PG8_BAR; PG8_SCHED;
	s_setprio 1
	s_waitcnt lgkmcnt(0)
	v_mfma_f32_16x16x32_bf16 v[60:63], v[128:131], v[198:201], v[60:63]
	v_mfma_f32_16x16x32_bf16 v[56:59], v[136:139], v[198:201], v[56:59]
	v_mfma_f32_16x16x32_bf16 v[48:51], v[128:131], v[206:209], v[48:51]
	v_mfma_f32_16x16x32_bf16 v[40:43], v[136:139], v[206:209], v[40:43]
	v_mfma_f32_16x16x32_bf16 v[32:35], v[128:131], v[214:217], v[32:35]
	s_add_i32 m0, s54, 0x2000
	v_lshl_add_u64 v[230:231], s[84:85], 0, v[150:151]
	global_load_lds_dwordx4 v[230:231], off
	v_mfma_f32_16x16x32_bf16 v[24:27], v[136:139], v[214:217], v[24:27]
	v_mfma_f32_16x16x32_bf16 v[16:19], v[128:131], v[222:225], v[16:19]
	v_mfma_f32_16x16x32_bf16 v[8:11], v[136:139], v[222:225], v[8:11]
	v_mfma_f32_16x16x32_bf16 v[60:63], v[132:135], v[202:205], v[60:63]
	v_mfma_f32_16x16x32_bf16 v[56:59], v[140:143], v[202:205], v[56:59]
	v_mfma_f32_16x16x32_bf16 v[48:51], v[132:135], v[210:213], v[48:51]
	v_mfma_f32_16x16x32_bf16 v[40:43], v[140:143], v[210:213], v[40:43]
	v_mfma_f32_16x16x32_bf16 v[32:35], v[132:135], v[218:221], v[32:35]
	s_mov_b32 m0, s53
	v_lshl_add_u64 v[230:231], s[44:45], 0, v[144:145]
	global_load_lds_dwordx4 v[230:231], off
	v_mfma_f32_16x16x32_bf16 v[24:27], v[140:143], v[218:221], v[24:27]
	v_mfma_f32_16x16x32_bf16 v[16:19], v[132:135], v[226:229], v[16:19]
	v_mfma_f32_16x16x32_bf16 v[8:11], v[140:143], v[226:229], v[8:11]
	s_setprio 0
	s_setprio 1
	v_mfma_f32_16x16x32_bf16 v[52:55], v[168:171], v[198:201], v[52:55]
	v_mfma_f32_16x16x32_bf16 v[44:47], v[190:193], v[198:201], v[44:47]
	v_mfma_f32_16x16x32_bf16 v[36:39], v[168:171], v[206:209], v[36:39]
	v_mfma_f32_16x16x32_bf16 v[28:31], v[190:193], v[206:209], v[28:31]
	v_mfma_f32_16x16x32_bf16 v[20:23], v[168:171], v[214:217], v[20:23]
	s_mov_b32 m0, s58
	s_nop 0
	global_load_lds_dwordx4 v[232:233], off
	v_mfma_f32_16x16x32_bf16 v[12:15], v[190:193], v[214:217], v[12:15]
	v_mfma_f32_16x16x32_bf16 v[4:7], v[168:171], v[222:225], v[4:7]
	v_mfma_f32_16x16x32_bf16 v[0:3], v[190:193], v[222:225], v[0:3]
	v_mfma_f32_16x16x32_bf16 v[52:55], v[182:185], v[202:205], v[52:55]
	v_mfma_f32_16x16x32_bf16 v[44:47], v[194:197], v[202:205], v[44:47]
	v_mfma_f32_16x16x32_bf16 v[36:39], v[182:185], v[210:213], v[36:39]
	v_mfma_f32_16x16x32_bf16 v[28:31], v[194:197], v[210:213], v[28:31]
	v_mfma_f32_16x16x32_bf16 v[20:23], v[182:185], v[218:221], v[20:23]
	v_mfma_f32_16x16x32_bf16 v[12:15], v[194:197], v[218:221], v[12:15]
	v_mfma_f32_16x16x32_bf16 v[4:7], v[182:185], v[226:229], v[4:7]
	v_mfma_f32_16x16x32_bf16 v[0:3], v[194:197], v[226:229], v[0:3]
	s_setprio 0
	s_barrier
	s_add_i32 s54, 0, 0x18000
	s_add_i32 s55, 0, 0x1c000
	v_add_u32_e32 v140, s54, v175
	v_add_u32_e32 v152, s55, v175
	ds_read_b128 v[128:131], v140
	ds_read_b128 v[132:135], v140 offset:1024
	ds_read_b128 v[136:139], v140 offset:2048
	ds_read_b128 v[140:143], v140 offset:3072
	ds_read_b128 v[168:171], v152
	ds_read_b128 v[182:185], v152 offset:1024
	ds_read_b128 v[190:193], v152 offset:2048
	ds_read_b128 v[194:197], v152 offset:3072
	s_add_u32 s44, s44, 0x40000
	s_addc_u32 s45, s45, 0
	s_mov_b32 m0, s59
	v_lshl_add_u64 v[234:235], s[44:45], 0, v[144:145]
	ds_read_b128 v[198:201], v179 offset:32768
	ds_read_b128 v[202:205], v179 offset:33792
	ds_read_b128 v[206:209], v179 offset:34816
	ds_read_b128 v[210:213], v179 offset:35840
	ds_read_b128 v[214:217], v179 offset:36864
	ds_read_b128 v[218:221], v179 offset:37888
	ds_read_b128 v[222:225], v179 offset:38912
	ds_read_b128 v[226:229], v179 offset:39936
	global_load_lds_dwordx4 v[234:235], off
	v_lshl_add_u64 v[234:235], s[44:45], 0, v[148:149]
	s_mov_b32 m0, s60
	s_nop 0
	global_load_lds_dwordx4 v[234:235], off
	s_waitcnt vmcnt(8)
	s_waitcnt lgkmcnt(0)
	s_barrier
	s_setprio 1
	s_waitcnt lgkmcnt(0)
	v_mfma_f32_16x16x32_bf16 v[124:127], v[128:131], v[198:201], v[124:127]
	v_mfma_f32_16x16x32_bf16 v[120:123], v[136:139], v[198:201], v[120:123]
	v_mfma_f32_16x16x32_bf16 v[108:111], v[128:131], v[206:209], v[108:111]
	v_mfma_f32_16x16x32_bf16 v[104:107], v[136:139], v[206:209], v[104:107]
	v_mfma_f32_16x16x32_bf16 v[96:99], v[128:131], v[214:217], v[96:99]
	v_mfma_f32_16x16x32_bf16 v[88:91], v[136:139], v[214:217], v[88:91]
	v_mfma_f32_16x16x32_bf16 v[80:83], v[128:131], v[222:225], v[80:83]
	v_mfma_f32_16x16x32_bf16 v[72:75], v[136:139], v[222:225], v[72:75]
	v_mfma_f32_16x16x32_bf16 v[124:127], v[132:135], v[202:205], v[124:127]
	v_mfma_f32_16x16x32_bf16 v[120:123], v[140:143], v[202:205], v[120:123]
	v_mfma_f32_16x16x32_bf16 v[108:111], v[132:135], v[210:213], v[108:111]
	v_mfma_f32_16x16x32_bf16 v[104:107], v[140:143], v[210:213], v[104:107]
	v_mfma_f32_16x16x32_bf16 v[96:99], v[132:135], v[218:221], v[96:99]
	v_mfma_f32_16x16x32_bf16 v[88:91], v[140:143], v[218:221], v[88:91]
	v_mfma_f32_16x16x32_bf16 v[80:83], v[132:135], v[226:229], v[80:83]
	v_mfma_f32_16x16x32_bf16 v[72:75], v[140:143], v[226:229], v[72:75]
	s_setprio 0
	s_setprio 1
	v_mfma_f32_16x16x32_bf16 v[116:119], v[168:171], v[198:201], v[116:119]
	v_mfma_f32_16x16x32_bf16 v[112:115], v[190:193], v[198:201], v[112:115]
	v_mfma_f32_16x16x32_bf16 v[100:103], v[168:171], v[206:209], v[100:103]
	v_mfma_f32_16x16x32_bf16 v[92:95], v[190:193], v[206:209], v[92:95]
	v_mfma_f32_16x16x32_bf16 v[84:87], v[168:171], v[214:217], v[84:87]
	v_mfma_f32_16x16x32_bf16 v[76:79], v[190:193], v[214:217], v[76:79]
	v_mfma_f32_16x16x32_bf16 v[68:71], v[168:171], v[222:225], v[68:71]
	v_mfma_f32_16x16x32_bf16 v[64:67], v[190:193], v[222:225], v[64:67]
	v_mfma_f32_16x16x32_bf16 v[116:119], v[182:185], v[202:205], v[116:119]
	v_mfma_f32_16x16x32_bf16 v[112:115], v[194:197], v[202:205], v[112:115]
	v_mfma_f32_16x16x32_bf16 v[100:103], v[182:185], v[210:213], v[100:103]
	v_mfma_f32_16x16x32_bf16 v[92:95], v[194:197], v[210:213], v[92:95]
	v_mfma_f32_16x16x32_bf16 v[84:87], v[182:185], v[218:221], v[84:87]
	v_mfma_f32_16x16x32_bf16 v[76:79], v[194:197], v[218:221], v[76:79]
	v_mfma_f32_16x16x32_bf16 v[68:71], v[182:185], v[226:229], v[68:71]
	v_mfma_f32_16x16x32_bf16 v[64:67], v[194:197], v[226:229], v[64:67]
	s_setprio 0
	s_barrier
; #define PG8_STAGE(bufoff, gbase, voff) do { _Pragma("unroll") for (int _i = 0; _i < 2; ++_i) \
;         __builtin_amdgcn_global_load_lds((const unsigned*)((const char*)(gbase) + (voff)[_i]), (PG8_LAS unsigned*)(lds + (bufoff) + ldsw + _i * 8192), 16, 0, 0); } while (0)
; #define PG8_LDA(dst, b, h) do { _Pragma("unroll") for (int m = 0; m < 4; ++m) _Pragma("unroll") for (int k = 0; k < 2; ++k) dst[m][k] = *(const PG8_LAS bf16x8*)(lds + PG8_SA(b, h) + aoff + m * 2048 + k * 1024); } while (0)
; #define PG8_MMA(ai, bj, At, Bt) do { __builtin_amdgcn_s_setprio(1); _Pragma("unroll") for (int m = 0; m < 4; ++m) _Pragma("unroll") for (int n = 0; n < 2; ++n) _Pragma("unroll") for (int k = 0; k < 2; ++k) \
;         acc[ai][bj][m][n] = __builtin_amdgcn_mfma_f32_16x16x32_bf16(Bt[n][k], At[m][k], acc[ai][bj][m][n], 0, 0, 0); __builtin_amdgcn_s_setprio(0); } while (0)
; #define PG8_WAIT_V(n) asm volatile("s_waitcnt vmcnt(" #n ")" ::: "memory")
; #define PG8_WAIT_L(n) asm volatile("s_waitcnt lgkmcnt(" #n ")" ::: "memory")
; #define PG8_BAR __builtin_amdgcn_s_barrier()
; #define PG8_SCHED __builtin_amdgcn_sched_barrier(0)
; template <class Epi, class Sched, bool ALIGN_EPI = false, bool SP2 = false>
; __device__ __forceinline__ void gemm_phase(PG8_LAS unsigned char* lds, const Gemm g, const Sched& S, const Epi& E) {
;     ...
;         for (int t = 0; t < nt; t += 2) {
;     ...
;             PG8_WAIT_V(8); PG8_WAIT_L(0); PG8_BAR; PG8_MMA(0, 0, At, B0); PG8_MMA(0, 1, At, B1); PG8_BAR; PG8_SCHED;
;             PG8_LDA(At, 1, 1); PG8_STAGE(PG8_SB(1, 0), b3, voffB); PG8_STAGE(PG8_SB(1, 1), b3 + hstep, voffB); PG8_STAGE(PG8_SA(1, 0), a3, voffA);
;             PG8_WAIT_V(8); PG8_WAIT_L(0); PG8_BAR; PG8_MMA(1, 0, At, B0); PG8_MMA(1, 1, At, B1); PG8_BAR; PG8_SCHED;
	s_add_i32 s44, s54, s50
	v_lshl_add_u64 v[172:173], v[172:173], 0, s[12:13]
	s_mov_b32 m0, s44
	ds_read_b128 v[198:201], v179 offset:49152
	ds_read_b128 v[202:205], v179 offset:50176
	ds_read_b128 v[206:209], v179 offset:51200
	ds_read_b128 v[210:213], v179 offset:52224
	ds_read_b128 v[214:217], v179 offset:53248
	ds_read_b128 v[218:221], v179 offset:54272
	ds_read_b128 v[222:225], v179 offset:55296
	ds_read_b128 v[226:229], v179 offset:56320
	global_load_lds_dwordx4 v[172:173], off
	s_add_i32 m0, s44, 0x2000
	s_add_u32 s42, s42, 0x40080
	v_lshl_add_u64 v[172:173], v[186:187], 0, s[12:13]
	s_addc_u32 s43, s43, 0
	s_add_i32 s44, s55, s50
	global_load_lds_dwordx4 v[172:173], off
	v_lshl_add_u64 v[172:173], s[42:43], 0, v[146:147]
	s_mov_b32 m0, s44
	s_nop 0
	global_load_lds_dwordx4 v[172:173], off
	s_waitcnt vmcnt(5)
	s_waitcnt lgkmcnt(0)
	s_barrier
	s_setprio 1
	s_waitcnt lgkmcnt(0)
	v_mfma_f32_16x16x32_bf16 v[60:63], v[128:131], v[198:201], v[60:63]
	v_mfma_f32_16x16x32_bf16 v[56:59], v[136:139], v[198:201], v[56:59]
	v_mfma_f32_16x16x32_bf16 v[48:51], v[128:131], v[206:209], v[48:51]
	v_mfma_f32_16x16x32_bf16 v[40:43], v[136:139], v[206:209], v[40:43]
	v_mfma_f32_16x16x32_bf16 v[32:35], v[128:131], v[214:217], v[32:35]
	s_add_i32 m0, s44, 0x2000
	v_lshl_add_u64 v[172:173], s[42:43], 0, v[150:151]
	global_load_lds_dwordx4 v[172:173], off
	v_mfma_f32_16x16x32_bf16 v[24:27], v[136:139], v[214:217], v[24:27]
	v_mfma_f32_16x16x32_bf16 v[16:19], v[128:131], v[222:225], v[16:19]
	v_mfma_f32_16x16x32_bf16 v[8:11], v[136:139], v[222:225], v[8:11]
	v_mfma_f32_16x16x32_bf16 v[60:63], v[132:135], v[202:205], v[60:63]
	v_mfma_f32_16x16x32_bf16 v[56:59], v[140:143], v[202:205], v[56:59]
	v_mfma_f32_16x16x32_bf16 v[48:51], v[132:135], v[210:213], v[48:51]
	v_mfma_f32_16x16x32_bf16 v[40:43], v[140:143], v[210:213], v[40:43]
	v_mfma_f32_16x16x32_bf16 v[32:35], v[132:135], v[218:221], v[32:35]
	s_mov_b32 m0, s62
	v_lshl_add_u64 v[172:173], v[230:231], 0, s[12:13]
	global_load_lds_dwordx4 v[172:173], off
	v_mfma_f32_16x16x32_bf16 v[24:27], v[140:143], v[218:221], v[24:27]
	v_mfma_f32_16x16x32_bf16 v[16:19], v[132:135], v[226:229], v[16:19]
	v_mfma_f32_16x16x32_bf16 v[8:11], v[140:143], v[226:229], v[8:11]
	s_setprio 0
	s_setprio 1
	v_mfma_f32_16x16x32_bf16 v[52:55], v[168:171], v[198:201], v[52:55]
	v_mfma_f32_16x16x32_bf16 v[44:47], v[190:193], v[198:201], v[44:47]
	v_mfma_f32_16x16x32_bf16 v[36:39], v[168:171], v[206:209], v[36:39]
	v_mfma_f32_16x16x32_bf16 v[28:31], v[190:193], v[206:209], v[28:31]
	v_mfma_f32_16x16x32_bf16 v[20:23], v[168:171], v[214:217], v[20:23]
	s_mov_b32 m0, s63
	v_lshl_add_u64 v[172:173], v[232:233], 0, s[12:13]
	global_load_lds_dwordx4 v[172:173], off
	v_mfma_f32_16x16x32_bf16 v[12:15], v[190:193], v[214:217], v[12:15]
	v_mfma_f32_16x16x32_bf16 v[4:7], v[168:171], v[222:225], v[4:7]
	v_mfma_f32_16x16x32_bf16 v[0:3], v[190:193], v[222:225], v[0:3]
	v_mfma_f32_16x16x32_bf16 v[52:55], v[182:185], v[202:205], v[52:55]
	v_mfma_f32_16x16x32_bf16 v[44:47], v[194:197], v[202:205], v[44:47]
	v_mfma_f32_16x16x32_bf16 v[36:39], v[182:185], v[210:213], v[36:39]
	v_mfma_f32_16x16x32_bf16 v[28:31], v[194:197], v[210:213], v[28:31]
	v_mfma_f32_16x16x32_bf16 v[20:23], v[182:185], v[218:221], v[20:23]
	v_mfma_f32_16x16x32_bf16 v[12:15], v[194:197], v[218:221], v[12:15]
	v_mfma_f32_16x16x32_bf16 v[4:7], v[182:185], v[226:229], v[4:7]
	v_mfma_f32_16x16x32_bf16 v[0:3], v[194:197], v[226:229], v[0:3]
	s_setprio 0
	s_barrier
	s_add_i32 vcc_hi, vcc_hi, 2
	s_add_u32 s40, s40, 0x100
	s_addc_u32 s41, s41, 0
	s_add_u32 s97, s97, 0x100
	s_addc_u32 vcc_lo, vcc_lo, 0
	s_cmp_gt_u32 vcc_hi, 13
	s_cbranch_scc0 .LBB0_126
	s_and_b64 vcc, exec, s[14:15]
	s_cbranch_vccz .LBB0_129
	s_barrier
